# v44 + decode queue hands out whole cache pages for the first two thirds of the tickets
# speedup vs baseline: 1.0083x; 1.0083x over previous
; #define LAS __attribute__((address_space(3)))
; __device__ __forceinline__ unsigned xb_add(unsigned* p, unsigned v) { return __hip_atomic_fetch_add(p, v, __ATOMIC_RELAXED, __HIP_MEMORY_SCOPE_AGENT); }
; __device__ __forceinline__ unsigned xb_xcc_id() { return (unsigned)__builtin_amdgcn_s_getreg((3 << 11) | 20) & 0xFu; }
; __device__ __forceinline__ XcdBarrier xcd_barrier_post(unsigned* bar, volatile LAS unsigned* st) {
;     XcdBarrier b; b.bar = bar; b.x = xb_xcc_id(); b.st = st;
;     if (threadIdx.x == 0) (void)xb_add(&bar[XB_XCNT(b.x)], 1u);
;     return b;
; __global__ void __launch_bounds__(512, 2) mk_fwd(Params P) {
;     extern __shared__ __attribute__((aligned(16))) unsigned char lds[];
;     volatile LAS unsigned* xbw = (volatile LAS unsigned*)((LAS unsigned char*)lds + LDS_CTL);
;     if (threadIdx.x < 4) xbw[threadIdx.x] = 0u;
;     __syncthreads();
;     XcdBarrier bar; bar.bar = (unsigned*)(P.ws + WS_BAR); bar.x = 0; bar.st = xbw;
;     ...
;     bar = xcd_barrier_post((unsigned*)(P.ws + WS_BAR), xbw);
_Z6mk_fwd6Params:
	s_load_dwordx8 s[68:75], s[0:1], 0xc0
	s_load_dwordx4 s[76:79], s[0:1], 0xe0
	s_load_dwordx2 s[60:61], s[0:1], 0xf0
	s_mov_b32 s56, s2
	s_mov_b32 s101, 0
	s_mov_b64 s[58:59], s[0:1]
	v_cmp_gt_u32_e32 vcc, 4, v0
	s_and_saveexec_b64 s[0:1], vcc
	v_lshl_add_u32 v1, v0, 2, 0
	v_add_u32_e32 v1, 0x26000, v1
	v_mov_b32_e32 v2, 0
	ds_write_b32 v1, v2
	s_or_b64 exec, exec, s[0:1]
	s_load_dwordx16 s[0:15], s[58:59], 0x0
	s_waitcnt lgkmcnt(0)
	s_barrier
	v_cmp_eq_u32_e64 s[80:81], 0, v0
	v_writelane_b32 v252, s0, 0
	s_nop 1
	v_writelane_b32 v252, s1, 1
	v_writelane_b32 v252, s2, 2
	v_writelane_b32 v252, s3, 3
	v_writelane_b32 v252, s4, 4
	v_writelane_b32 v252, s5, 5
	v_writelane_b32 v252, s6, 6
	v_writelane_b32 v252, s7, 7
	v_writelane_b32 v252, s8, 8
	v_writelane_b32 v252, s9, 9
	v_writelane_b32 v252, s10, 10
	v_writelane_b32 v252, s11, 11
	v_writelane_b32 v252, s12, 12
	v_writelane_b32 v252, s13, 13
	v_writelane_b32 v252, s14, 14
	v_writelane_b32 v252, s15, 15
	s_getreg_b32 s0, hwreg(HW_REG_XCC_ID, 0, 4)
	s_and_b32 s57, s0, 15
	s_and_saveexec_b64 s[0:1], s[80:81]
	s_cbranch_execz .LBB0_5
	s_mov_b64 s[2:3], exec
	v_mbcnt_lo_u32_b32 v1, s2, 0
	v_mbcnt_hi_u32_b32 v1, s3, v1
	v_cmp_eq_u32_e32 vcc, 0, v1
	s_and_b64 s[4:5], exec, vcc
	s_mov_b64 exec, s[4:5]
	s_cbranch_execz .LBB0_5
	s_lshl_b32 s4, s57, 8
	s_bcnt1_i32_b64 s2, s[2:3]
	v_mov_b32_e32 v1, s4
	v_mov_b32_e32 v2, s2
	global_atomic_add v1, v2, s[78:79] offset:1024

; #define LAS __attribute__((address_space(3)))
; __device__ __forceinline__ unsigned xb_ld(unsigned* p)              { return __hip_atomic_load(p, __ATOMIC_RELAXED, __HIP_MEMORY_SCOPE_AGENT); }
; #define XB_SPIN(cond, bar) do { unsigned _sp = 0; while (cond) { __builtin_amdgcn_s_sleep(1); \
;     if ((++_sp & 255u) == 0u) { if (xb_ld(&(bar)[XB_TMO])) break; if (_sp > XB_SPIN_CAP) { atomicAdd(&(bar)[XB_TMO], 1u); break; } } } } while (0)
; __device__ __forceinline__ void sb_decode_wave_loop(const Params& P, float* lds) {
;     unsigned* qd = (unsigned*)(P.ws + WS_BAR) + QW_DEC;
;     const int lane = threadIdx.x & 63;
;     volatile LAS unsigned* scw = (volatile LAS unsigned*)((LAS unsigned char*)lds + SC_CTL_OFF_FWD);
;     unsigned nxt = 0u;
;     if (lane == 0) nxt = atomicAdd(qd, 2u);
; __device__ __forceinline__ void p3_scan_and_sb(const Params& P, float* lds) {
;     const int tid = threadIdx.x, lane = tid & 63, wave = tid >> 6;
;     unsigned* ctl = (unsigned*)(P.ws + WS_BAR);
;     __syncthreads();
;     if (blockIdx.x < 96) {
;         const int bh = blockIdx.x >> 2, quarter = blockIdx.x & 3, b = bh / RH, h = bh % RH;
;         volatile LAS unsigned* scw = (volatile LAS unsigned*)((LAS unsigned char*)lds + SC_CTL_OFF);
;         if (tid < 5) scw[tid] = 0u;
;         if (tid == 0) { XB_SPIN(xb_ld(ctl + QW_PREP_W) < (unsigned)NPREP, ctl); __builtin_amdgcn_fence(__ATOMIC_ACQUIRE, "agent"); asm volatile("s_waitcnt vmcnt(0)" ::: "memory"); }
;         __syncthreads();
;         scan_prompt_wave(P, (unsigned char*)lds, b, h, quarter);
;         if (wave >= 5 + SC_FREE_WAVES) {
;             constexpr unsigned NCHU = SEQ / SCH;
;             while (scw[1] < NCHU || scw[2] < NCHU || scw[3] < NCHU || scw[4] < NCHU) __builtin_amdgcn_s_sleep(32);
;         }
;     } else {
;         const int grp = wave >> 2, gw = wave & 3;
;         volatile LAS unsigned* gctl = (volatile LAS unsigned*)((LAS unsigned char*)lds + LDS_CTL + 32);
;         if (tid < 8) gctl[tid] = 0u;
;         __syncthreads();
;         sba::Grp4 G; G.ctr = gctl + grp; G.gen = 0u;
;         if (grp == 1) sb_decode_wave_loop(P, lds);
.LBB0_939:
	s_cmp_lt_i32 s60, 4
	s_cselect_b64 s[0:1], -1, 0
	s_cmp_gt_i32 s61, 3
	s_cselect_b64 s[2:3], -1, 0
	s_and_b64 s[34:35], s[0:1], s[2:3]
	s_andn2_b64 vcc, exec, s[34:35]
	s_cbranch_vccnz .LBB0_1576
	v_writelane_b32 v252, s34, 54
	s_cmpk_lt_u32 s56, 0x60
	v_and_b32_e32 v1, 63, v0
	v_writelane_b32 v252, s35, 55
	v_writelane_b32 v252, s80, 56
	s_cselect_b64 s[52:53], -1, 0
	s_cmpk_gt_u32 s56, 0x5f
	v_writelane_b32 v252, s81, 57
	v_writelane_b32 v252, s56, 53
	v_writelane_b32 v252, s60, 51
	s_mov_b64 s[0:1], -1
	s_waitcnt vmcnt(0)
	v_writelane_b32 v252, s61, 52
	s_barrier
	v_writelane_b32 v252, s57, 50
	s_cbranch_scc0 .LBB0_1203
	v_writelane_b32 v252, s52, 58
	v_cmp_gt_u32_e32 vcc, 8, v0
	s_nop 0
	v_writelane_b32 v252, s53, 59
	s_and_saveexec_b64 s[0:1], vcc
	v_lshl_add_u32 v2, v0, 2, 0
	v_add_u32_e32 v2, 0x26020, v2
	v_mov_b32_e32 v3, 0
	ds_write_b32 v2, v3
	s_or_b64 exec, exec, s[0:1]
	v_lshrrev_b32_e32 v94, 8, v0
	s_waitcnt lgkmcnt(0)
	s_barrier
	v_cmp_eq_u32_e32 vcc, 1, v94
	s_mov_b64 s[0:1], exec
	v_writelane_b32 v252, s0, 60
	s_nop 1
	v_writelane_b32 v252, s1, 61
	s_cmpk_gt_u32 s56, 0xaa
	s_cselect_b64 s[2:3], exec, 0
	s_or_b64 vcc, vcc, s[2:3]
	s_and_b64 s[0:1], s[0:1], vcc
	s_mov_b64 exec, s[0:1]
	s_cbranch_execz .LBB0_1092
	v_readfirstlane_b32 s2, v94
	s_cmp_eq_u32 s2, 0
	s_cselect_b32 s100, 1, 0x7fffffff
	s_add_u32 s0, s78, 0x3900
	s_addc_u32 s1, s79, 0
	v_writelane_b32 v252, s0, 62
	v_mov_b32_e32 v95, 0
	v_cmp_eq_u32_e64 s[4:5], 0, v1
	v_writelane_b32 v252, s1, 63
	s_and_saveexec_b64 s[0:1], s[4:5]
	v_readlane_b32 s22, v252, 48
	v_readlane_b32 s23, v252, 49
	s_cbranch_execz .LBB0_948
	s_mov_b64 s[6:7], exec
	v_mbcnt_lo_u32_b32 v2, s6, 0
	v_mbcnt_hi_u32_b32 v2, s7, v2
	v_cmp_eq_u32_e32 vcc, 0, v2
	s_and_saveexec_b64 s[2:3], vcc
	s_cbranch_execz .LBB0_947
	s_bcnt1_i32_b64 s6, s[6:7]
	s_mul_i32 s6, s6, 6
	s_mov_b32 s99, 3
	v_mov_b32_e32 v4, s6
	v_readlane_b32 s6, v252, 62
	v_mov_b32_e32 v3, 0
	v_readlane_b32 s7, v252, 63
	s_nop 4
	global_atomic_add v3, v3, v4, s[6:7] sc0

; __device__ __forceinline__ void sb_decode_wave_loop(const Params& P, float* lds) {
;     ...
;     for (;;) {
;         const int t = __builtin_amdgcn_readfirstlane((int)nxt);
;         if (t >= DEC_NTASK) break;
;         if (lane == 0) nxt = atomicAdd(qd, 2u);
;         bool thin = false;
;         bool scan_running = false;
;         if (SC_THIN && blockIdx.x < 96) { constexpr unsigned NCHU = SEQ / 16; scan_running = scw[1] < NCHU || scw[2] < NCHU || scw[3] < NCHU || scw[4] < NCHU; thin = scan_running; }
;         thin = true;
;         if (blockIdx.x < 96 && scan_running) { sb_decode_task<4>(P, lds, t); sb_decode_task<4>(P, lds, t + 1); }
;         else if (thin) { sb_decode_task<8>(P, lds, t); sb_decode_task<8>(P, lds, t + 1); }
;         else { sb_decode_task<16>(P, lds, t); sb_decode_task<16>(P, lds, t + 1); }
;     }
.LBB0_949:
	s_or_b64 exec, exec, s[0:1]
	s_mov_b64 s[0:1], 0
	s_add_i32 s101, s101, 1
	s_cmp_lt_u32 s101, s98
	s_cbranch_scc0 .Lsx1_next
	s_add_i32 s34, s34, 1
	s_cmpk_gt_i32 s34, 0x5fff
	s_cbranch_scc1 .Lsx1_next
	s_branch .LBB0_956
.Lsx1_next:
	s_mov_b32 s101, 0

; __device__ __forceinline__ void sb_decode_wave_loop(const Params& P, float* lds) {
;     ...
;     for (;;) {
;         const int t = __builtin_amdgcn_readfirstlane((int)nxt);
;         if (t >= DEC_NTASK) break;
;         if (lane == 0) nxt = atomicAdd(qd, 2u);
.LBB0_951:
	v_readfirstlane_b32 s34, v95
	s_cmpk_gt_i32 s34, 0x5fff
	s_mov_b64 s[0:1], -1
	s_cbranch_scc1 .LBB0_950
	s_mov_b32 s98, s99
	s_cmpk_lt_i32 s34, 0x4000
	s_cselect_b32 s99, 3, 1
	s_cmp_eq_u32 s100, 0
	s_cbranch_scc1 .Ledc_last
	s_sub_i32 s100, s100, 1
	s_and_saveexec_b64 s[0:1], s[4:5]
	s_cbranch_execz .LBB0_956
	s_mov_b64 s[36:37], exec
	v_mbcnt_lo_u32_b32 v2, s36, 0
	v_mbcnt_hi_u32_b32 v2, s37, v2
	v_cmp_eq_u32_e32 vcc, 0, v2
	s_and_saveexec_b64 s[2:3], vcc
	s_cbranch_execz .LBB0_955
	s_bcnt1_i32_b64 s33, s[36:37]
	s_mul_i32 s33, s33, s99
	s_lshl_b32 s33, s33, 1
	v_readlane_b32 s36, v252, 62
	v_mov_b32_e32 v3, s33
	v_readlane_b32 s37, v252, 63
	s_nop 4
	global_atomic_add v3, v83, v3, s[36:37] sc0

; __device__ __forceinline__ void sb_decode_wave_loop(const Params& P, float* lds) {
;     ...
;     for (;;) {
;         const int t = __builtin_amdgcn_readfirstlane((int)nxt);
;         if (t >= DEC_NTASK) break;
;         if (lane == 0) nxt = atomicAdd(qd, 2u);
;         bool thin = false;
;         bool scan_running = false;
;         if (SC_THIN && blockIdx.x < 96) { constexpr unsigned NCHU = SEQ / 16; scan_running = scw[1] < NCHU || scw[2] < NCHU || scw[3] < NCHU || scw[4] < NCHU; thin = scan_running; }
;         thin = true;
;         if (blockIdx.x < 96 && scan_running) { sb_decode_task<4>(P, lds, t); sb_decode_task<4>(P, lds, t + 1); }
;         else if (thin) { sb_decode_task<8>(P, lds, t); sb_decode_task<8>(P, lds, t + 1); }
;         else { sb_decode_task<16>(P, lds, t); sb_decode_task<16>(P, lds, t + 1); }
;     }
.LBB0_1267:
	s_mov_b64 s[0:1], 0
	s_add_i32 s101, s101, 1
	s_cmp_lt_u32 s101, s98
	s_cbranch_scc0 .Lsx2_next
	s_add_i32 s34, s34, 2
	s_cmpk_gt_i32 s34, 0x5fff
	s_cbranch_scc1 .Lsx2_next
	s_branch .LBB0_1274

; __device__ __forceinline__ void sb_decode_wave_loop(const Params& P, float* lds) {
;     ...
;     for (;;) {
;         const int t = __builtin_amdgcn_readfirstlane((int)nxt);
;         if (t >= DEC_NTASK) break;
;         if (lane == 0) nxt = atomicAdd(qd, 2u);
.LBB0_1269:
	v_readfirstlane_b32 s34, v98
	s_cmpk_gt_i32 s34, 0x5fff
	s_mov_b64 s[0:1], -1
	s_cbranch_scc1 .LBB0_1268
	s_mov_b32 s98, s99
	s_cmpk_lt_i32 s34, 0x4000
	s_cselect_b32 s99, 3, 1
	s_and_saveexec_b64 s[0:1], s[4:5]
	s_cbranch_execz .LBB0_1274
	s_mov_b64 s[36:37], exec
	v_mbcnt_lo_u32_b32 v2, s36, 0
	v_mbcnt_hi_u32_b32 v2, s37, v2
	v_cmp_eq_u32_e32 vcc, 0, v2
	s_and_saveexec_b64 s[2:3], vcc
	s_cbranch_execz .LBB0_1273
	s_bcnt1_i32_b64 s33, s[36:37]
	s_mul_i32 s33, s33, s99
	s_lshl_b32 s33, s33, 1
	v_readlane_b32 s30, v252, 62
	v_mov_b32_e32 v3, s33
	v_readlane_b32 s31, v252, 63
	s_nop 4
	global_atomic_add v3, v83, v3, s[30:31] sc0
